# adds: nt (streaming) hint on the pure-output f32 stores never re-read on chip (new_diff_k/new_diff_v tiles of the input GEMM, y of the MLP-down GEMM): 96 store sites
# baseline (speedup 1.0000x reference)
; __device__ __forceinline__ void ld_bf8(const bf16* p, f32x4& a, f32x4& b) { const u32x4 w = *(const u32x4*)p; a = (f32x4){bflo(w.x), bfhi(w.x), bflo(w.y), bfhi(w.y)}; b = (f32x4){bflo(w.z), bfhi(w.z), bflo(w.w), bfhi(w.w)}; }
;     __device__ __forceinline__ void operator()(AccRef acc, const pg8::Unit& u, int wr, int wc, int fr, int fq) const {
;         const int c0 = u.pn * 256;
;         EPI_LOOP_P( if (row < nvalid) { f32x4 b0, b1; ld_bf8(XB + rw * 1024 + c0 + cl, b0, b1); float* p = y + rw * 1024 + c0 + cl; *(f32x4*)p = b0 + v0; *(f32x4*)(p + 4) = b1 + v1; } )
;     }
.LBB0_241:
	s_lshl_b32 s20, s47, 8
	s_ashr_i32 s21, s20, 31
	v_lshl_add_u32 v144, s48, 8, v137
	v_ashrrev_i32_e32 v145, 31, v144
	v_lshlrev_b64 v[148:149], 11, v[144:145]
	v_lshl_add_u64 v[148:149], s[12:13], 0, v[148:149]
	v_lshl_add_u64 v[148:149], s[20:21], 1, v[148:149]
	v_lshlrev_b32_e32 v184, 1, v136
	v_lshl_add_u64 v[148:149], v[148:149], 0, v[184:185]
	s_mov_b64 vcc, 0x8000
	s_mov_b64 s[22:23], 0x28000
	global_load_dwordx4 v[160:163], v[148:149], off
	global_load_dwordx4 v[164:167], v[148:149], off offset:256
	v_lshl_add_u64 v[148:149], v[148:149], 0, vcc
	global_load_dwordx4 v[168:171], v[148:149], off
	global_load_dwordx4 v[172:175], v[148:149], off offset:256
	v_lshl_add_u64 v[148:149], v[148:149], 0, vcc
	global_load_dwordx4 v[176:179], v[148:149], off
	global_load_dwordx4 v[180:183], v[148:149], off offset:256
	v_lshl_add_u64 v[148:149], v[148:149], 0, vcc
	global_load_dwordx4 v[190:193], v[148:149], off
	global_load_dwordx4 v[196:199], v[148:149], off offset:256
	v_lshl_add_u64 v[148:149], v[148:149], 0, s[22:23]
	global_load_dwordx4 v[200:203], v[148:149], off
	global_load_dwordx4 v[212:215], v[148:149], off offset:256
	v_lshl_add_u64 v[148:149], v[148:149], 0, vcc
	global_load_dwordx4 v[216:219], v[148:149], off
	global_load_dwordx4 v[220:223], v[148:149], off offset:256
	v_lshl_add_u64 v[148:149], v[148:149], 0, vcc
	global_load_dwordx4 v[224:227], v[148:149], off
	global_load_dwordx4 v[228:231], v[148:149], off offset:256
	v_lshl_add_u64 v[148:149], v[148:149], 0, vcc
	global_load_dwordx4 v[232:235], v[148:149], off
	global_load_dwordx4 v[236:239], v[148:149], off offset:256
	s_lshl_b32 s20, s47, 8
	v_lshl_add_u32 v144, s48, 8, v137
	s_ashr_i32 s21, s20, 31
	v_cmp_gt_i32_e32 vcc, s24, v144
	v_lshlrev_b32_e32 v184, 1, v136
	v_lshlrev_b32_e32 v142, 2, v136
	s_and_saveexec_b64 s[22:23], vcc
	s_cbranch_execz .LBB0_243
	v_ashrrev_i32_e32 v145, 31, v144
	v_lshlrev_b64 v[148:149], 11, v[144:145]
	v_lshl_add_u64 v[148:149], s[12:13], 0, v[148:149]
	v_lshl_add_u64 v[148:149], s[20:21], 1, v[148:149]
	v_lshl_add_u64 v[152:153], v[148:149], 0, v[184:185]
	v_lshlrev_b64 v[154:155], 12, v[144:145]
	v_lshl_add_u64 v[154:155], s[10:11], 0, v[154:155]
	v_mov_b32_e32 v143, v185
	v_lshl_add_u64 v[154:155], s[20:21], 2, v[154:155]
	v_lshl_add_u64 v[154:155], v[154:155], 0, v[142:143]
	s_waitcnt vmcnt(15)
	v_lshlrev_b32_e32 v156, 16, v160
	v_and_b32_e32 v157, 0xffff0000, v160
	v_lshlrev_b32_e32 v148, 16, v161
	v_and_b32_e32 v149, 0xffff0000, v161
	v_lshlrev_b32_e32 v158, 16, v162
	v_and_b32_e32 v159, 0xffff0000, v162
	v_lshlrev_b32_e32 v150, 16, v163
	v_and_b32_e32 v151, 0xffff0000, v163
	v_pk_add_f32 v[126:127], v[126:127], v[148:149]
	v_pk_add_f32 v[124:125], v[124:125], v[156:157]
	v_pk_add_f32 v[122:123], v[122:123], v[150:151]
	v_pk_add_f32 v[120:121], v[120:121], v[158:159]
	global_store_dwordx4 v[154:155], v[124:127], off nt
	global_store_dwordx4 v[154:155], v[120:123], off offset:16 nt
	s_nop 1
	s_waitcnt vmcnt(16)
	v_lshlrev_b32_e32 v124, 16, v164
	v_and_b32_e32 v125, 0xffff0000, v164
	v_lshlrev_b32_e32 v120, 16, v165
	v_and_b32_e32 v121, 0xffff0000, v165
	v_lshlrev_b32_e32 v126, 16, v166
	v_and_b32_e32 v127, 0xffff0000, v166
	v_lshlrev_b32_e32 v122, 16, v167
	v_and_b32_e32 v123, 0xffff0000, v167
	v_pk_add_f32 v[118:119], v[118:119], v[120:121]
	v_pk_add_f32 v[116:117], v[116:117], v[124:125]
	v_pk_add_f32 v[114:115], v[114:115], v[122:123]
	v_pk_add_f32 v[112:113], v[112:113], v[126:127]
	global_store_dwordx4 v[154:155], v[116:119], off offset:512 nt
	global_store_dwordx4 v[154:155], v[112:115], off offset:528 nt
.LBB0_243:
	s_or_b64 exec, exec, s[22:23]
	s_nop 0
	v_or_b32_e32 v112, 16, v144
	v_cmp_gt_i32_e32 vcc, s24, v112
	s_and_saveexec_b64 s[22:23], vcc
	s_cbranch_execz .LBB0_245
	v_ashrrev_i32_e32 v113, 31, v112
	v_lshlrev_b64 v[114:115], 11, v[112:113]
	v_lshl_add_u64 v[114:115], s[12:13], 0, v[114:115]
	v_lshl_add_u64 v[114:115], s[20:21], 1, v[114:115]
	v_lshl_add_u64 v[118:119], v[114:115], 0, v[184:185]
	v_lshlrev_b64 v[112:113], 12, v[112:113]
	v_lshl_add_u64 v[112:113], s[10:11], 0, v[112:113]
	v_mov_b32_e32 v143, v185
	v_lshl_add_u64 v[112:113], s[20:21], 2, v[112:113]
	v_lshl_add_u64 v[112:113], v[112:113], 0, v[142:143]
	s_waitcnt vmcnt(17)
	v_lshlrev_b32_e32 v120, 16, v168
	v_and_b32_e32 v121, 0xffff0000, v168
	v_lshlrev_b32_e32 v114, 16, v169
	v_and_b32_e32 v115, 0xffff0000, v169
	v_lshlrev_b32_e32 v122, 16, v170
	v_and_b32_e32 v123, 0xffff0000, v170
	v_lshlrev_b32_e32 v116, 16, v171
	v_and_b32_e32 v117, 0xffff0000, v171
	v_pk_add_f32 v[110:111], v[110:111], v[114:115]
	v_pk_add_f32 v[108:109], v[108:109], v[120:121]
	v_pk_add_f32 v[106:107], v[106:107], v[116:117]
	v_pk_add_f32 v[104:105], v[104:105], v[122:123]
	global_store_dwordx4 v[112:113], v[108:111], off nt
	global_store_dwordx4 v[112:113], v[104:107], off offset:16 nt
	s_nop 1
	s_waitcnt vmcnt(18)
	v_lshlrev_b32_e32 v108, 16, v172
	v_and_b32_e32 v109, 0xffff0000, v172
	v_lshlrev_b32_e32 v104, 16, v173
	v_and_b32_e32 v105, 0xffff0000, v173
	v_lshlrev_b32_e32 v110, 16, v174
	v_and_b32_e32 v111, 0xffff0000, v174
	v_lshlrev_b32_e32 v106, 16, v175
	v_and_b32_e32 v107, 0xffff0000, v175
	v_pk_add_f32 v[102:103], v[102:103], v[104:105]
	v_pk_add_f32 v[100:101], v[100:101], v[108:109]
	v_pk_add_f32 v[98:99], v[98:99], v[106:107]
	v_pk_add_f32 v[96:97], v[96:97], v[110:111]
	global_store_dwordx4 v[112:113], v[100:103], off offset:512 nt
	global_store_dwordx4 v[112:113], v[96:99], off offset:528 nt
; __device__ __forceinline__ void ld_bf8(const bf16* p, f32x4& a, f32x4& b) { const u32x4 w = *(const u32x4*)p; a = (f32x4){bflo(w.x), bfhi(w.x), bflo(w.y), bfhi(w.y)}; b = (f32x4){bflo(w.z), bfhi(w.z), bflo(w.w), bfhi(w.w)}; }
;     __device__ __forceinline__ void operator()(AccRef acc, const pg8::Unit& u, int wr, int wc, int fr, int fq) const {
;         const int c0 = u.pn * 256;
;         EPI_LOOP_P( if (row < nvalid) { f32x4 b0, b1; ld_bf8(XB + rw * 1024 + c0 + cl, b0, b1); float* p = y + rw * 1024 + c0 + cl; *(f32x4*)p = b0 + v0; *(f32x4*)(p + 4) = b1 + v1; } )
;     }
.LBB0_245:
	s_or_b64 exec, exec, s[22:23]
	s_nop 0
	v_or_b32_e32 v96, 32, v144
	v_cmp_gt_i32_e32 vcc, s24, v96
	s_and_saveexec_b64 s[22:23], vcc
	s_cbranch_execz .LBB0_247
	v_ashrrev_i32_e32 v97, 31, v96
	v_lshlrev_b64 v[98:99], 11, v[96:97]
	v_lshl_add_u64 v[98:99], s[12:13], 0, v[98:99]
	v_lshl_add_u64 v[98:99], s[20:21], 1, v[98:99]
	v_lshl_add_u64 v[102:103], v[98:99], 0, v[184:185]
	v_lshlrev_b64 v[96:97], 12, v[96:97]
	v_lshl_add_u64 v[96:97], s[10:11], 0, v[96:97]
	v_mov_b32_e32 v143, v185
	v_lshl_add_u64 v[96:97], s[20:21], 2, v[96:97]
	v_lshl_add_u64 v[96:97], v[96:97], 0, v[142:143]
	s_waitcnt vmcnt(19)
	v_lshlrev_b32_e32 v104, 16, v176
	v_and_b32_e32 v105, 0xffff0000, v176
	v_lshlrev_b32_e32 v98, 16, v177
	v_and_b32_e32 v99, 0xffff0000, v177
	v_lshlrev_b32_e32 v106, 16, v178
	v_and_b32_e32 v107, 0xffff0000, v178
	v_lshlrev_b32_e32 v100, 16, v179
	v_and_b32_e32 v101, 0xffff0000, v179
	v_pk_add_f32 v[94:95], v[94:95], v[98:99]
	v_pk_add_f32 v[92:93], v[92:93], v[104:105]
	v_pk_add_f32 v[90:91], v[90:91], v[100:101]
	v_pk_add_f32 v[88:89], v[88:89], v[106:107]
	global_store_dwordx4 v[96:97], v[92:95], off nt
	global_store_dwordx4 v[96:97], v[88:91], off offset:16 nt
	s_nop 1
	s_waitcnt vmcnt(20)
	v_lshlrev_b32_e32 v92, 16, v180
	v_and_b32_e32 v93, 0xffff0000, v180
	v_lshlrev_b32_e32 v88, 16, v181
	v_and_b32_e32 v89, 0xffff0000, v181
	v_lshlrev_b32_e32 v94, 16, v182
	v_and_b32_e32 v95, 0xffff0000, v182
	v_lshlrev_b32_e32 v90, 16, v183
	v_and_b32_e32 v91, 0xffff0000, v183
	v_pk_add_f32 v[86:87], v[86:87], v[88:89]
	v_pk_add_f32 v[84:85], v[84:85], v[92:93]
	v_pk_add_f32 v[82:83], v[82:83], v[90:91]
	v_pk_add_f32 v[80:81], v[80:81], v[94:95]
	global_store_dwordx4 v[96:97], v[84:87], off offset:512 nt
	global_store_dwordx4 v[96:97], v[80:83], off offset:528 nt
.LBB0_247:
	s_or_b64 exec, exec, s[22:23]
	s_nop 0
	v_or_b32_e32 v80, 48, v144
	v_cmp_gt_i32_e32 vcc, s24, v80
	s_and_saveexec_b64 s[22:23], vcc
	s_cbranch_execz .LBB0_249
	v_ashrrev_i32_e32 v81, 31, v80
	v_lshlrev_b64 v[82:83], 11, v[80:81]
	v_lshl_add_u64 v[82:83], s[12:13], 0, v[82:83]
	v_lshl_add_u64 v[82:83], s[20:21], 1, v[82:83]
	v_lshl_add_u64 v[86:87], v[82:83], 0, v[184:185]
	v_lshlrev_b64 v[80:81], 12, v[80:81]
	v_lshl_add_u64 v[80:81], s[10:11], 0, v[80:81]
	v_mov_b32_e32 v143, v185
	v_lshl_add_u64 v[80:81], s[20:21], 2, v[80:81]
	v_lshl_add_u64 v[80:81], v[80:81], 0, v[142:143]
	s_waitcnt vmcnt(21)
	v_lshlrev_b32_e32 v88, 16, v190
	v_and_b32_e32 v89, 0xffff0000, v190
	v_lshlrev_b32_e32 v82, 16, v191
	v_and_b32_e32 v83, 0xffff0000, v191
	v_lshlrev_b32_e32 v90, 16, v192
	v_and_b32_e32 v91, 0xffff0000, v192
	v_lshlrev_b32_e32 v84, 16, v193
	v_and_b32_e32 v85, 0xffff0000, v193
	v_pk_add_f32 v[78:79], v[78:79], v[82:83]
	v_pk_add_f32 v[76:77], v[76:77], v[88:89]
	v_pk_add_f32 v[74:75], v[74:75], v[84:85]
	v_pk_add_f32 v[72:73], v[72:73], v[90:91]
	global_store_dwordx4 v[80:81], v[76:79], off nt
	global_store_dwordx4 v[80:81], v[72:75], off offset:16 nt
	s_nop 1
	s_waitcnt vmcnt(22)
	v_lshlrev_b32_e32 v76, 16, v196
	v_and_b32_e32 v77, 0xffff0000, v196
	v_lshlrev_b32_e32 v72, 16, v197
	v_and_b32_e32 v73, 0xffff0000, v197
	v_lshlrev_b32_e32 v78, 16, v198
	v_and_b32_e32 v79, 0xffff0000, v198
	v_lshlrev_b32_e32 v74, 16, v199
	v_and_b32_e32 v75, 0xffff0000, v199
	v_pk_add_f32 v[70:71], v[70:71], v[72:73]
	v_pk_add_f32 v[68:69], v[68:69], v[76:77]
	v_pk_add_f32 v[66:67], v[66:67], v[74:75]
	v_pk_add_f32 v[64:65], v[64:65], v[78:79]
	global_store_dwordx4 v[80:81], v[68:71], off offset:512 nt
	global_store_dwordx4 v[80:81], v[64:67], off offset:528 nt
.LBB0_249:
	s_or_b64 exec, exec, s[22:23]
	s_nop 0
	v_add_u32_e32 v64, 0x80, v144
	v_cmp_gt_i32_e32 vcc, s24, v64
	s_and_saveexec_b64 s[22:23], vcc
	s_cbranch_execz .LBB0_251
	v_ashrrev_i32_e32 v65, 31, v64
	v_lshlrev_b64 v[66:67], 11, v[64:65]
	v_lshl_add_u64 v[66:67], s[12:13], 0, v[66:67]
	v_lshl_add_u64 v[66:67], s[20:21], 1, v[66:67]
	v_lshl_add_u64 v[70:71], v[66:67], 0, v[184:185]
	v_lshlrev_b64 v[64:65], 12, v[64:65]
	v_lshl_add_u64 v[64:65], s[10:11], 0, v[64:65]
	v_mov_b32_e32 v143, v185
	v_lshl_add_u64 v[64:65], s[20:21], 2, v[64:65]
	v_lshl_add_u64 v[64:65], v[64:65], 0, v[142:143]
	s_waitcnt vmcnt(23)
	v_lshlrev_b32_e32 v72, 16, v200
	v_and_b32_e32 v73, 0xffff0000, v200
	v_lshlrev_b32_e32 v66, 16, v201
	v_and_b32_e32 v67, 0xffff0000, v201
	v_lshlrev_b32_e32 v74, 16, v202
	v_and_b32_e32 v75, 0xffff0000, v202
	v_lshlrev_b32_e32 v68, 16, v203
	v_and_b32_e32 v69, 0xffff0000, v203
	v_pk_add_f32 v[62:63], v[62:63], v[66:67]
	v_pk_add_f32 v[60:61], v[60:61], v[72:73]
	v_pk_add_f32 v[58:59], v[58:59], v[68:69]
	v_pk_add_f32 v[56:57], v[56:57], v[74:75]
	global_store_dwordx4 v[64:65], v[60:63], off nt
	global_store_dwordx4 v[64:65], v[56:59], off offset:16 nt
	s_nop 1
	s_waitcnt vmcnt(24)
	v_lshlrev_b32_e32 v60, 16, v212
	v_and_b32_e32 v61, 0xffff0000, v212
	v_lshlrev_b32_e32 v56, 16, v213
	v_and_b32_e32 v57, 0xffff0000, v213
	v_lshlrev_b32_e32 v62, 16, v214
	v_and_b32_e32 v63, 0xffff0000, v214
	v_lshlrev_b32_e32 v58, 16, v215
	v_and_b32_e32 v59, 0xffff0000, v215
	v_pk_add_f32 v[54:55], v[54:55], v[56:57]
	v_pk_add_f32 v[52:53], v[52:53], v[60:61]
	v_pk_add_f32 v[50:51], v[50:51], v[58:59]
	v_pk_add_f32 v[48:49], v[48:49], v[62:63]
	global_store_dwordx4 v[64:65], v[52:55], off offset:512 nt
	global_store_dwordx4 v[64:65], v[48:51], off offset:528 nt
; __device__ __forceinline__ void ld_bf8(const bf16* p, f32x4& a, f32x4& b) { const u32x4 w = *(const u32x4*)p; a = (f32x4){bflo(w.x), bfhi(w.x), bflo(w.y), bfhi(w.y)}; b = (f32x4){bflo(w.z), bfhi(w.z), bflo(w.w), bfhi(w.w)}; }
;     __device__ __forceinline__ void operator()(AccRef acc, const pg8::Unit& u, int wr, int wc, int fr, int fq) const {
;         const int c0 = u.pn * 256;
;         EPI_LOOP_P( if (row < nvalid) { f32x4 b0, b1; ld_bf8(XB + rw * 1024 + c0 + cl, b0, b1); float* p = y + rw * 1024 + c0 + cl; *(f32x4*)p = b0 + v0; *(f32x4*)(p + 4) = b1 + v1; } )
;     }
.LBB0_251:
	s_or_b64 exec, exec, s[22:23]
	s_nop 0
	v_add_u32_e32 v48, 0x90, v144
	v_cmp_gt_i32_e32 vcc, s24, v48
	s_and_saveexec_b64 s[22:23], vcc
	s_cbranch_execz .LBB0_253
	v_ashrrev_i32_e32 v49, 31, v48
	v_lshlrev_b64 v[50:51], 11, v[48:49]
	v_lshl_add_u64 v[50:51], s[12:13], 0, v[50:51]
	v_lshl_add_u64 v[50:51], s[20:21], 1, v[50:51]
	v_lshl_add_u64 v[54:55], v[50:51], 0, v[184:185]
	v_lshlrev_b64 v[48:49], 12, v[48:49]
	v_lshl_add_u64 v[48:49], s[10:11], 0, v[48:49]
	v_mov_b32_e32 v143, v185
	v_lshl_add_u64 v[48:49], s[20:21], 2, v[48:49]
	v_lshl_add_u64 v[48:49], v[48:49], 0, v[142:143]
	s_waitcnt vmcnt(25)
	v_lshlrev_b32_e32 v56, 16, v216
	v_and_b32_e32 v57, 0xffff0000, v216
	v_lshlrev_b32_e32 v50, 16, v217
	v_and_b32_e32 v51, 0xffff0000, v217
	v_lshlrev_b32_e32 v58, 16, v218
	v_and_b32_e32 v59, 0xffff0000, v218
	v_lshlrev_b32_e32 v52, 16, v219
	v_and_b32_e32 v53, 0xffff0000, v219
	v_pk_add_f32 v[46:47], v[46:47], v[50:51]
	v_pk_add_f32 v[44:45], v[44:45], v[56:57]
	v_pk_add_f32 v[42:43], v[42:43], v[52:53]
	v_pk_add_f32 v[40:41], v[40:41], v[58:59]
	global_store_dwordx4 v[48:49], v[44:47], off nt
	global_store_dwordx4 v[48:49], v[40:43], off offset:16 nt
	s_nop 1
	s_waitcnt vmcnt(26)
	v_lshlrev_b32_e32 v44, 16, v220
	v_and_b32_e32 v45, 0xffff0000, v220
	v_lshlrev_b32_e32 v40, 16, v221
	v_and_b32_e32 v41, 0xffff0000, v221
	v_lshlrev_b32_e32 v46, 16, v222
	v_and_b32_e32 v47, 0xffff0000, v222
	v_lshlrev_b32_e32 v42, 16, v223
	v_and_b32_e32 v43, 0xffff0000, v223
	v_pk_add_f32 v[38:39], v[38:39], v[40:41]
	v_pk_add_f32 v[36:37], v[36:37], v[44:45]
	v_pk_add_f32 v[34:35], v[34:35], v[42:43]
	v_pk_add_f32 v[32:33], v[32:33], v[46:47]
	global_store_dwordx4 v[48:49], v[36:39], off offset:512 nt
	global_store_dwordx4 v[48:49], v[32:35], off offset:528 nt
.LBB0_253:
	s_or_b64 exec, exec, s[22:23]
	s_nop 0
	v_add_u32_e32 v32, 0xa0, v144
	v_cmp_gt_i32_e32 vcc, s24, v32
	s_and_saveexec_b64 s[22:23], vcc
	s_cbranch_execz .LBB0_255
	v_ashrrev_i32_e32 v33, 31, v32
	v_lshlrev_b64 v[34:35], 11, v[32:33]
	v_lshl_add_u64 v[34:35], s[12:13], 0, v[34:35]
	v_lshl_add_u64 v[34:35], s[20:21], 1, v[34:35]
	v_lshl_add_u64 v[38:39], v[34:35], 0, v[184:185]
	v_lshlrev_b64 v[32:33], 12, v[32:33]
	v_lshl_add_u64 v[32:33], s[10:11], 0, v[32:33]
	v_mov_b32_e32 v143, v185
	v_lshl_add_u64 v[32:33], s[20:21], 2, v[32:33]
	v_lshl_add_u64 v[32:33], v[32:33], 0, v[142:143]
	s_waitcnt vmcnt(27)
	v_lshlrev_b32_e32 v40, 16, v224
	v_and_b32_e32 v41, 0xffff0000, v224
	v_lshlrev_b32_e32 v34, 16, v225
	v_and_b32_e32 v35, 0xffff0000, v225
	v_lshlrev_b32_e32 v42, 16, v226
	v_and_b32_e32 v43, 0xffff0000, v226
	v_lshlrev_b32_e32 v36, 16, v227
	v_and_b32_e32 v37, 0xffff0000, v227
	v_pk_add_f32 v[30:31], v[30:31], v[34:35]
	v_pk_add_f32 v[28:29], v[28:29], v[40:41]
	v_pk_add_f32 v[26:27], v[26:27], v[36:37]
	v_pk_add_f32 v[24:25], v[24:25], v[42:43]
	global_store_dwordx4 v[32:33], v[28:31], off nt
	global_store_dwordx4 v[32:33], v[24:27], off offset:16 nt
	s_nop 1
	s_waitcnt vmcnt(28)
	v_lshlrev_b32_e32 v28, 16, v228
	v_and_b32_e32 v29, 0xffff0000, v228
	v_lshlrev_b32_e32 v24, 16, v229
	v_and_b32_e32 v25, 0xffff0000, v229
	v_lshlrev_b32_e32 v30, 16, v230
	v_and_b32_e32 v31, 0xffff0000, v230
	v_lshlrev_b32_e32 v26, 16, v231
	v_and_b32_e32 v27, 0xffff0000, v231
	v_pk_add_f32 v[22:23], v[22:23], v[24:25]
	v_pk_add_f32 v[20:21], v[20:21], v[28:29]
	v_pk_add_f32 v[18:19], v[18:19], v[26:27]
	v_pk_add_f32 v[16:17], v[16:17], v[30:31]
	global_store_dwordx4 v[32:33], v[20:23], off offset:512 nt
	global_store_dwordx4 v[32:33], v[16:19], off offset:528 nt
.LBB0_255:
	s_or_b64 exec, exec, s[22:23]
	s_nop 0
	v_add_u32_e32 v16, 0xb0, v144
	v_cmp_gt_i32_e32 vcc, s24, v16
	s_and_saveexec_b64 s[22:23], vcc
	s_cbranch_execz .LBB0_257
	v_ashrrev_i32_e32 v17, 31, v16
	v_lshlrev_b64 v[18:19], 11, v[16:17]
	v_lshl_add_u64 v[18:19], s[12:13], 0, v[18:19]
	v_lshl_add_u64 v[18:19], s[20:21], 1, v[18:19]
	v_lshl_add_u64 v[22:23], v[18:19], 0, v[184:185]
	v_lshlrev_b64 v[16:17], 12, v[16:17]
	v_lshl_add_u64 v[16:17], s[10:11], 0, v[16:17]
	v_mov_b32_e32 v143, v185
	v_lshl_add_u64 v[16:17], s[20:21], 2, v[16:17]
	v_lshl_add_u64 v[16:17], v[16:17], 0, v[142:143]
	s_waitcnt vmcnt(29)
	v_lshlrev_b32_e32 v24, 16, v232
	v_and_b32_e32 v25, 0xffff0000, v232
	v_lshlrev_b32_e32 v18, 16, v233
	v_and_b32_e32 v19, 0xffff0000, v233
	v_lshlrev_b32_e32 v26, 16, v234
	v_and_b32_e32 v27, 0xffff0000, v234
	v_lshlrev_b32_e32 v20, 16, v235
	v_and_b32_e32 v21, 0xffff0000, v235
	v_pk_add_f32 v[14:15], v[14:15], v[18:19]
	v_pk_add_f32 v[12:13], v[12:13], v[24:25]
	v_pk_add_f32 v[10:11], v[10:11], v[20:21]
	v_pk_add_f32 v[8:9], v[8:9], v[26:27]
	global_store_dwordx4 v[16:17], v[12:15], off nt
	global_store_dwordx4 v[16:17], v[8:11], off offset:16 nt
	s_nop 1
	s_waitcnt vmcnt(30)
	v_lshlrev_b32_e32 v12, 16, v236
	v_and_b32_e32 v13, 0xffff0000, v236
	v_lshlrev_b32_e32 v8, 16, v237
	v_and_b32_e32 v9, 0xffff0000, v237
	v_lshlrev_b32_e32 v14, 16, v238
	v_and_b32_e32 v15, 0xffff0000, v238
	v_lshlrev_b32_e32 v10, 16, v239
	v_and_b32_e32 v11, 0xffff0000, v239
	v_pk_add_f32 v[6:7], v[6:7], v[8:9]
	v_pk_add_f32 v[4:5], v[4:5], v[12:13]
	v_pk_add_f32 v[2:3], v[2:3], v[10:11]
	v_pk_add_f32 v[0:1], v[0:1], v[14:15]
	global_store_dwordx4 v[16:17], v[4:7], off offset:512 nt
	global_store_dwordx4 v[16:17], v[0:3], off offset:528 nt

; __device__ __forceinline__ void st_bf8(bf16* p, f32x4 a, f32x4 b) { u32x4 w; w.x = pk2(a[0], a[1]); w.y = pk2(a[2], a[3]); w.z = pk2(b[0], b[1]); w.w = pk2(b[2], b[3]); *(u32x4*)p = w; }
;     __device__ __forceinline__ void operator()(AccRef acc, const pg8::Unit& u, int wr, int wc, int fr, int fq) const {
;     ...
;         else if (t < 12) { const int c0 = (t - 8) * 256; EPI_LOOP_P( st_bf8(VD + rw * 1024 + c0 + cl, v0, v1); if (row < nvalid) { float* o = ovd + rw * 1024 + c0 + cl; *(f32x4*)o = v0; *(f32x4*)(o + 4) = v1; } ) }
.LBB0_803:
	s_andn2_b64 vcc, exec, s[22:23]
	s_cbranch_vccnz .LBB0_837
	s_lshl_b32 s38, s74, 8
	v_add_u32_e32 v134, s38, v145
	v_ashrrev_i32_e32 v135, 31, v134
	s_lshl_b32 s22, s75, 8
	v_lshlrev_b64 v[128:129], 11, v[134:135]
	s_add_i32 s66, s22, 0xfffff800
	v_lshl_add_u64 v[128:129], s[14:15], 0, v[128:129]
	v_lshl_add_u64 v[128:129], s[66:67], 1, v[128:129]
	v_lshlrev_b32_e32 v184, 1, v144
	v_lshlrev_b64 v[152:153], 10, v[134:135]
	v_lshl_add_u64 v[128:129], v[128:129], 0, v[184:185]
	v_cvt_pk_bf16_f32 v130, v124, v125
	v_cvt_pk_bf16_f32 v131, v126, v127
	v_cvt_pk_bf16_f32 v132, v120, v121
	v_cvt_pk_bf16_f32 v133, v122, v123
	global_store_dwordx4 v[128:129], v[130:133], off
	v_cmp_gt_i32_e32 vcc, s41, v134
	s_nop 0
	v_lshl_add_u64 v[130:131], v[152:153], 2, s[6:7]
	s_and_saveexec_b64 s[22:23], vcc
	s_cbranch_execz .LBB0_806
	v_lshl_add_u64 v[132:133], s[66:67], 2, v[130:131]
	v_lshlrev_b32_e32 v134, 2, v144
	v_mov_b32_e32 v135, v185
	v_lshl_add_u64 v[132:133], v[132:133], 0, v[134:135]
	global_store_dwordx4 v[132:133], v[124:127], off nt
	global_store_dwordx4 v[132:133], v[120:123], off offset:16 nt
.LBB0_806:
	s_or_b64 exec, exec, s[22:23]
	v_cvt_pk_bf16_f32 v132, v116, v117
	v_cvt_pk_bf16_f32 v133, v118, v119
	v_cvt_pk_bf16_f32 v134, v112, v113
	v_cvt_pk_bf16_f32 v135, v114, v115
	global_store_dwordx4 v[128:129], v[132:135], off offset:256
	s_and_saveexec_b64 s[22:23], vcc
	s_cbranch_execz .LBB0_808
	v_lshl_add_u64 v[128:129], s[66:67], 2, v[130:131]
	v_lshlrev_b32_e32 v130, 2, v144
	v_mov_b32_e32 v131, v185
	v_lshl_add_u64 v[128:129], v[128:129], 0, v[130:131]
	global_store_dwordx4 v[128:129], v[116:119], off offset:512 nt
	global_store_dwordx4 v[128:129], v[112:115], off offset:528 nt
.LBB0_808:
	s_or_b64 exec, exec, s[22:23]
	v_add_u32_e32 v134, s38, v180
	v_ashrrev_i32_e32 v135, 31, v134
	v_lshlrev_b64 v[128:129], 11, v[134:135]
	v_lshl_add_u64 v[128:129], s[14:15], 0, v[128:129]
	v_lshl_add_u64 v[128:129], s[66:67], 1, v[128:129]
	v_lshlrev_b64 v[152:153], 10, v[134:135]
	v_lshl_add_u64 v[128:129], v[128:129], 0, v[184:185]
	v_cvt_pk_bf16_f32 v130, v108, v109
	v_cvt_pk_bf16_f32 v131, v110, v111
	v_cvt_pk_bf16_f32 v132, v104, v105
	v_cvt_pk_bf16_f32 v133, v106, v107
	global_store_dwordx4 v[128:129], v[130:133], off
	v_cmp_gt_i32_e32 vcc, s41, v134
	s_nop 0
	v_lshl_add_u64 v[130:131], v[152:153], 2, s[6:7]
	s_and_saveexec_b64 s[22:23], vcc
	s_cbranch_execz .LBB0_810
	v_lshl_add_u64 v[132:133], s[66:67], 2, v[130:131]
	v_lshlrev_b32_e32 v134, 2, v144
	v_mov_b32_e32 v135, v185
	v_lshl_add_u64 v[132:133], v[132:133], 0, v[134:135]
	global_store_dwordx4 v[132:133], v[108:111], off nt
	global_store_dwordx4 v[132:133], v[104:107], off offset:16 nt
.LBB0_810:
	s_or_b64 exec, exec, s[22:23]
	v_cvt_pk_bf16_f32 v132, v100, v101
	v_cvt_pk_bf16_f32 v133, v102, v103
	v_cvt_pk_bf16_f32 v134, v96, v97
	v_cvt_pk_bf16_f32 v135, v98, v99
	global_store_dwordx4 v[128:129], v[132:135], off offset:256
	s_and_saveexec_b64 s[22:23], vcc
	s_cbranch_execz .LBB0_812
	v_lshl_add_u64 v[128:129], s[66:67], 2, v[130:131]
	v_lshlrev_b32_e32 v130, 2, v144
	v_mov_b32_e32 v131, v185
	v_lshl_add_u64 v[128:129], v[128:129], 0, v[130:131]
	global_store_dwordx4 v[128:129], v[100:103], off offset:512 nt
	global_store_dwordx4 v[128:129], v[96:99], off offset:528 nt
.LBB0_812:
	s_or_b64 exec, exec, s[22:23]
	v_add_u32_e32 v134, s38, v181
	v_ashrrev_i32_e32 v135, 31, v134
	v_lshlrev_b64 v[128:129], 11, v[134:135]
	v_lshl_add_u64 v[128:129], s[14:15], 0, v[128:129]
	v_lshl_add_u64 v[128:129], s[66:67], 1, v[128:129]
	v_lshlrev_b64 v[152:153], 10, v[134:135]
	v_lshl_add_u64 v[128:129], v[128:129], 0, v[184:185]
	v_cvt_pk_bf16_f32 v130, v92, v93
	v_cvt_pk_bf16_f32 v131, v94, v95
	v_cvt_pk_bf16_f32 v132, v88, v89
	v_cvt_pk_bf16_f32 v133, v90, v91
	global_store_dwordx4 v[128:129], v[130:133], off
	v_cmp_gt_i32_e32 vcc, s41, v134
	s_nop 0
	v_lshl_add_u64 v[130:131], v[152:153], 2, s[6:7]
	s_and_saveexec_b64 s[22:23], vcc
	s_cbranch_execz .LBB0_814
	v_lshl_add_u64 v[132:133], s[66:67], 2, v[130:131]
	v_lshlrev_b32_e32 v134, 2, v144
	v_mov_b32_e32 v135, v185
	v_lshl_add_u64 v[132:133], v[132:133], 0, v[134:135]
	global_store_dwordx4 v[132:133], v[92:95], off nt
	global_store_dwordx4 v[132:133], v[88:91], off offset:16 nt
.LBB0_814:
	s_or_b64 exec, exec, s[22:23]
	v_cvt_pk_bf16_f32 v132, v84, v85
	v_cvt_pk_bf16_f32 v133, v86, v87
	v_cvt_pk_bf16_f32 v134, v80, v81
	v_cvt_pk_bf16_f32 v135, v82, v83
	global_store_dwordx4 v[128:129], v[132:135], off offset:256
	s_and_saveexec_b64 s[22:23], vcc
	s_cbranch_execz .LBB0_816
	v_lshl_add_u64 v[128:129], s[66:67], 2, v[130:131]
	v_lshlrev_b32_e32 v130, 2, v144
	v_mov_b32_e32 v131, v185
	v_lshl_add_u64 v[128:129], v[128:129], 0, v[130:131]
	global_store_dwordx4 v[128:129], v[84:87], off offset:512 nt
	global_store_dwordx4 v[128:129], v[80:83], off offset:528 nt
.LBB0_816:
	s_or_b64 exec, exec, s[22:23]
	v_add_u32_e32 v134, s38, v182
	v_ashrrev_i32_e32 v135, 31, v134
	v_lshlrev_b64 v[128:129], 11, v[134:135]
	v_lshl_add_u64 v[128:129], s[14:15], 0, v[128:129]
	v_lshl_add_u64 v[128:129], s[66:67], 1, v[128:129]
	v_lshlrev_b64 v[152:153], 10, v[134:135]
	v_lshl_add_u64 v[128:129], v[128:129], 0, v[184:185]
	v_cvt_pk_bf16_f32 v130, v76, v77
	v_cvt_pk_bf16_f32 v131, v78, v79
	v_cvt_pk_bf16_f32 v132, v72, v73
	v_cvt_pk_bf16_f32 v133, v74, v75
	global_store_dwordx4 v[128:129], v[130:133], off
	v_cmp_gt_i32_e32 vcc, s41, v134
	s_nop 0
	v_lshl_add_u64 v[130:131], v[152:153], 2, s[6:7]
	s_and_saveexec_b64 s[22:23], vcc
	s_cbranch_execz .LBB0_818
	v_lshl_add_u64 v[132:133], s[66:67], 2, v[130:131]
	v_lshlrev_b32_e32 v134, 2, v144
	v_mov_b32_e32 v135, v185
	v_lshl_add_u64 v[132:133], v[132:133], 0, v[134:135]
	global_store_dwordx4 v[132:133], v[76:79], off nt
	global_store_dwordx4 v[132:133], v[72:75], off offset:16 nt
; __device__ __forceinline__ void st_bf8(bf16* p, f32x4 a, f32x4 b) { u32x4 w; w.x = pk2(a[0], a[1]); w.y = pk2(a[2], a[3]); w.z = pk2(b[0], b[1]); w.w = pk2(b[2], b[3]); *(u32x4*)p = w; }
;     __device__ __forceinline__ void operator()(AccRef acc, const pg8::Unit& u, int wr, int wc, int fr, int fq) const {
;     ...
;         else if (t < 12) { const int c0 = (t - 8) * 256; EPI_LOOP_P( st_bf8(VD + rw * 1024 + c0 + cl, v0, v1); if (row < nvalid) { float* o = ovd + rw * 1024 + c0 + cl; *(f32x4*)o = v0; *(f32x4*)(o + 4) = v1; } ) }
.LBB0_818:
	s_or_b64 exec, exec, s[22:23]
	v_cvt_pk_bf16_f32 v132, v68, v69
	v_cvt_pk_bf16_f32 v133, v70, v71
	v_cvt_pk_bf16_f32 v134, v64, v65
	v_cvt_pk_bf16_f32 v135, v66, v67
	global_store_dwordx4 v[128:129], v[132:135], off offset:256
	s_and_saveexec_b64 s[22:23], vcc
	s_cbranch_execz .LBB0_820
	v_lshl_add_u64 v[128:129], s[66:67], 2, v[130:131]
	v_lshlrev_b32_e32 v130, 2, v144
	v_mov_b32_e32 v131, v185
	v_lshl_add_u64 v[128:129], v[128:129], 0, v[130:131]
	global_store_dwordx4 v[128:129], v[68:71], off offset:512 nt
	global_store_dwordx4 v[128:129], v[64:67], off offset:528 nt
.LBB0_820:
	s_or_b64 exec, exec, s[22:23]
	v_add_u32_e32 v134, s38, v183
	v_ashrrev_i32_e32 v135, 31, v134
	v_lshlrev_b64 v[128:129], 11, v[134:135]
	v_lshl_add_u64 v[128:129], s[14:15], 0, v[128:129]
	v_lshl_add_u64 v[128:129], s[66:67], 1, v[128:129]
	v_lshlrev_b64 v[152:153], 10, v[134:135]
	v_lshl_add_u64 v[128:129], v[128:129], 0, v[184:185]
	v_cvt_pk_bf16_f32 v130, v60, v61
	v_cvt_pk_bf16_f32 v131, v62, v63
	v_cvt_pk_bf16_f32 v132, v56, v57
	v_cvt_pk_bf16_f32 v133, v58, v59
	global_store_dwordx4 v[128:129], v[130:133], off
	v_cmp_gt_i32_e32 vcc, s41, v134
	s_nop 0
	v_lshl_add_u64 v[130:131], v[152:153], 2, s[6:7]
	s_and_saveexec_b64 s[22:23], vcc
	s_cbranch_execz .LBB0_822
	v_lshl_add_u64 v[132:133], s[66:67], 2, v[130:131]
	v_lshlrev_b32_e32 v134, 2, v144
	v_mov_b32_e32 v135, v185
	v_lshl_add_u64 v[132:133], v[132:133], 0, v[134:135]
	global_store_dwordx4 v[132:133], v[60:63], off nt
	global_store_dwordx4 v[132:133], v[56:59], off offset:16 nt
.LBB0_822:
	s_or_b64 exec, exec, s[22:23]
	v_cvt_pk_bf16_f32 v132, v52, v53
	v_cvt_pk_bf16_f32 v133, v54, v55
	v_cvt_pk_bf16_f32 v134, v48, v49
	v_cvt_pk_bf16_f32 v135, v50, v51
	global_store_dwordx4 v[128:129], v[132:135], off offset:256
	s_and_saveexec_b64 s[22:23], vcc
	s_cbranch_execz .LBB0_824
	v_lshl_add_u64 v[128:129], s[66:67], 2, v[130:131]
	v_lshlrev_b32_e32 v130, 2, v144
	v_mov_b32_e32 v131, v185
	v_lshl_add_u64 v[128:129], v[128:129], 0, v[130:131]
	global_store_dwordx4 v[128:129], v[52:55], off offset:512 nt
	global_store_dwordx4 v[128:129], v[48:51], off offset:528 nt
.LBB0_824:
	s_or_b64 exec, exec, s[22:23]
	v_add_u32_e32 v134, s38, v190
	v_ashrrev_i32_e32 v135, 31, v134
	v_lshlrev_b64 v[128:129], 11, v[134:135]
	v_lshl_add_u64 v[128:129], s[14:15], 0, v[128:129]
	v_lshl_add_u64 v[128:129], s[66:67], 1, v[128:129]
	v_lshlrev_b64 v[152:153], 10, v[134:135]
	v_lshl_add_u64 v[128:129], v[128:129], 0, v[184:185]
	v_cvt_pk_bf16_f32 v130, v44, v45
	v_cvt_pk_bf16_f32 v131, v46, v47
	v_cvt_pk_bf16_f32 v132, v40, v41
	v_cvt_pk_bf16_f32 v133, v42, v43
	global_store_dwordx4 v[128:129], v[130:133], off
	v_cmp_gt_i32_e32 vcc, s41, v134
	s_nop 0
	v_lshl_add_u64 v[130:131], v[152:153], 2, s[6:7]
	s_and_saveexec_b64 s[22:23], vcc
	s_cbranch_execz .LBB0_826
	v_lshl_add_u64 v[132:133], s[66:67], 2, v[130:131]
	v_lshlrev_b32_e32 v134, 2, v144
	v_mov_b32_e32 v135, v185
	v_lshl_add_u64 v[132:133], v[132:133], 0, v[134:135]
	global_store_dwordx4 v[132:133], v[44:47], off nt
	global_store_dwordx4 v[132:133], v[40:43], off offset:16 nt
.LBB0_826:
	s_or_b64 exec, exec, s[22:23]
	v_cvt_pk_bf16_f32 v132, v36, v37
	v_cvt_pk_bf16_f32 v133, v38, v39
	v_cvt_pk_bf16_f32 v134, v32, v33
	v_cvt_pk_bf16_f32 v135, v34, v35
	global_store_dwordx4 v[128:129], v[132:135], off offset:256
	s_and_saveexec_b64 s[22:23], vcc
	s_cbranch_execz .LBB0_828
	v_lshl_add_u64 v[128:129], s[66:67], 2, v[130:131]
	v_lshlrev_b32_e32 v130, 2, v144
	v_mov_b32_e32 v131, v185
	v_lshl_add_u64 v[128:129], v[128:129], 0, v[130:131]
	global_store_dwordx4 v[128:129], v[36:39], off offset:512 nt
	global_store_dwordx4 v[128:129], v[32:35], off offset:528 nt
.LBB0_828:
	s_or_b64 exec, exec, s[22:23]
	v_add_u32_e32 v134, s38, v191
	v_ashrrev_i32_e32 v135, 31, v134
	v_lshlrev_b64 v[128:129], 11, v[134:135]
	v_lshl_add_u64 v[128:129], s[14:15], 0, v[128:129]
	v_lshl_add_u64 v[128:129], s[66:67], 1, v[128:129]
	v_lshlrev_b64 v[152:153], 10, v[134:135]
	v_lshl_add_u64 v[128:129], v[128:129], 0, v[184:185]
	v_cvt_pk_bf16_f32 v130, v28, v29
	v_cvt_pk_bf16_f32 v131, v30, v31
	v_cvt_pk_bf16_f32 v132, v24, v25
	v_cvt_pk_bf16_f32 v133, v26, v27
	global_store_dwordx4 v[128:129], v[130:133], off
	v_cmp_gt_i32_e32 vcc, s41, v134
	s_nop 0
	v_lshl_add_u64 v[130:131], v[152:153], 2, s[6:7]
	s_and_saveexec_b64 s[22:23], vcc
	s_cbranch_execz .LBB0_830
	v_lshl_add_u64 v[132:133], s[66:67], 2, v[130:131]
	v_lshlrev_b32_e32 v134, 2, v144
	v_mov_b32_e32 v135, v185
	v_lshl_add_u64 v[132:133], v[132:133], 0, v[134:135]
	global_store_dwordx4 v[132:133], v[28:31], off nt
	global_store_dwordx4 v[132:133], v[24:27], off offset:16 nt
.LBB0_830:
	s_or_b64 exec, exec, s[22:23]
	v_cvt_pk_bf16_f32 v132, v20, v21
	v_cvt_pk_bf16_f32 v133, v22, v23
	v_cvt_pk_bf16_f32 v134, v16, v17
	v_cvt_pk_bf16_f32 v135, v18, v19
	global_store_dwordx4 v[128:129], v[132:135], off offset:256
	s_and_saveexec_b64 s[22:23], vcc
	s_cbranch_execz .LBB0_832
	v_lshl_add_u64 v[128:129], s[66:67], 2, v[130:131]
	v_lshlrev_b32_e32 v130, 2, v144
	v_mov_b32_e32 v131, v185
	v_lshl_add_u64 v[128:129], v[128:129], 0, v[130:131]
	global_store_dwordx4 v[128:129], v[20:23], off offset:512 nt
	global_store_dwordx4 v[128:129], v[16:19], off offset:528 nt
.LBB0_832:
	s_or_b64 exec, exec, s[22:23]
	v_add_u32_e32 v134, s38, v192
	v_ashrrev_i32_e32 v135, 31, v134
	v_lshlrev_b64 v[128:129], 11, v[134:135]
	v_lshl_add_u64 v[128:129], s[14:15], 0, v[128:129]
	v_lshl_add_u64 v[128:129], s[66:67], 1, v[128:129]
	v_lshlrev_b64 v[152:153], 10, v[134:135]
	v_lshl_add_u64 v[128:129], v[128:129], 0, v[184:185]
	v_cvt_pk_bf16_f32 v130, v12, v13
	v_cvt_pk_bf16_f32 v131, v14, v15
	v_cvt_pk_bf16_f32 v132, v8, v9
	v_cvt_pk_bf16_f32 v133, v10, v11
	global_store_dwordx4 v[128:129], v[130:133], off
	v_cmp_gt_i32_e32 vcc, s41, v134
	s_nop 0
	v_lshl_add_u64 v[130:131], v[152:153], 2, s[6:7]
	s_and_saveexec_b64 s[22:23], vcc
	s_cbranch_execz .LBB0_834
	v_lshl_add_u64 v[132:133], s[66:67], 2, v[130:131]
	v_lshlrev_b32_e32 v184, 2, v144
	v_lshl_add_u64 v[132:133], v[132:133], 0, v[184:185]
	global_store_dwordx4 v[132:133], v[12:15], off nt
	global_store_dwordx4 v[132:133], v[8:11], off offset:16 nt
.LBB0_834:
	s_or_b64 exec, exec, s[22:23]
	v_cvt_pk_bf16_f32 v132, v4, v5
	v_cvt_pk_bf16_f32 v133, v6, v7
	v_cvt_pk_bf16_f32 v134, v0, v1
	v_cvt_pk_bf16_f32 v135, v2, v3
	global_store_dwordx4 v[128:129], v[132:135], off offset:256
	s_and_saveexec_b64 s[22:23], vcc
	s_cbranch_execz .LBB0_836
	v_lshl_add_u64 v[128:129], s[66:67], 2, v[130:131]
	v_lshlrev_b32_e32 v184, 2, v144
	v_lshl_add_u64 v[128:129], v[128:129], 0, v[184:185]
	global_store_dwordx4 v[128:129], v[4:7], off offset:512 nt
	global_store_dwordx4 v[128:129], v[0:3], off offset:528 nt

; __device__ __forceinline__ unsigned pk2(float lo, float hi) { f32x2 v = {lo, hi}; bf16x2_hw b = __builtin_convertvector(v, bf16x2_hw); return __builtin_bit_cast(unsigned, b); }
; __device__ __forceinline__ void st_bf8(bf16* p, f32x4 a, f32x4 b) { u32x4 w; w.x = pk2(a[0], a[1]); w.y = pk2(a[2], a[3]); w.z = pk2(b[0], b[1]); w.w = pk2(b[2], b[3]); *(u32x4*)p = w; }
;     __device__ __forceinline__ void operator()(AccRef acc, const pg8::Unit& u, int wr, int wc, int fr, int fq) const {
;     ...
;         else if (t < 8) { const int c0 = (t - 4) * 256; EPI_LOOP_P( st_bf8(KD + rw * 1024 + c0 + cl, v0, v1); if (row < nvalid) { float* o = okd + rw * 1024 + c0 + cl; *(f32x4*)o = v0; *(f32x4*)(o + 4) = v1; } ) }
.LBB0_838:
	s_andn2_b64 vcc, exec, s[22:23]
	s_cbranch_vccnz .LBB0_872
	s_lshl_b32 s38, s74, 8
	v_add_u32_e32 v128, s38, v145
	v_ashrrev_i32_e32 v129, 31, v128
	s_lshl_b32 s22, s75, 8
	v_lshlrev_b64 v[130:131], 11, v[128:129]
	s_add_i32 s66, s22, 0xfffffc00
	v_lshl_add_u64 v[130:131], s[12:13], 0, v[130:131]
	v_lshl_add_u64 v[130:131], s[66:67], 1, v[130:131]
	v_lshlrev_b32_e32 v184, 1, v144
	v_lshlrev_b64 v[152:153], 10, v[128:129]
	v_lshl_add_u64 v[130:131], v[130:131], 0, v[184:185]
	v_cvt_pk_bf16_f32 v132, v124, v125
	v_cvt_pk_bf16_f32 v133, v126, v127
	v_cvt_pk_bf16_f32 v134, v120, v121
	v_cvt_pk_bf16_f32 v135, v122, v123
	global_store_dwordx4 v[130:131], v[132:135], off
	v_cmp_gt_i32_e32 vcc, s41, v128
	v_lshlrev_b32_e32 v128, 2, v144
	v_lshl_add_u64 v[132:133], v[152:153], 2, s[4:5]
	s_and_saveexec_b64 s[22:23], vcc
	s_cbranch_execz .LBB0_841
	v_lshl_add_u64 v[134:135], s[66:67], 2, v[132:133]
	v_mov_b32_e32 v129, v185
	v_lshl_add_u64 v[134:135], v[134:135], 0, v[128:129]
	global_store_dwordx4 v[134:135], v[124:127], off nt
	global_store_dwordx4 v[134:135], v[120:123], off offset:16 nt
.LBB0_841:
	s_or_b64 exec, exec, s[22:23]
	v_cvt_pk_bf16_f32 v152, v116, v117
	v_cvt_pk_bf16_f32 v153, v118, v119
	v_cvt_pk_bf16_f32 v154, v112, v113
	v_cvt_pk_bf16_f32 v155, v114, v115
	global_store_dwordx4 v[130:131], v[152:155], off offset:256
	s_and_saveexec_b64 s[22:23], vcc
	s_cbranch_execz .LBB0_843
	v_lshl_add_u64 v[130:131], s[66:67], 2, v[132:133]
	v_mov_b32_e32 v129, v185
	v_lshl_add_u64 v[130:131], v[130:131], 0, v[128:129]
	global_store_dwordx4 v[130:131], v[116:119], off offset:512 nt
	global_store_dwordx4 v[130:131], v[112:115], off offset:528 nt
.LBB0_843:
	s_or_b64 exec, exec, s[22:23]
	v_add_u32_e32 v152, s38, v180
	v_ashrrev_i32_e32 v153, 31, v152
	v_lshlrev_b64 v[130:131], 11, v[152:153]
	v_lshl_add_u64 v[130:131], s[12:13], 0, v[130:131]
	v_lshl_add_u64 v[130:131], s[66:67], 1, v[130:131]
	v_lshlrev_b64 v[154:155], 10, v[152:153]
	v_lshl_add_u64 v[130:131], v[130:131], 0, v[184:185]
	v_cvt_pk_bf16_f32 v132, v108, v109
	v_cvt_pk_bf16_f32 v133, v110, v111
	v_cvt_pk_bf16_f32 v134, v104, v105
	v_cvt_pk_bf16_f32 v135, v106, v107
	global_store_dwordx4 v[130:131], v[132:135], off
	v_cmp_gt_i32_e32 vcc, s41, v152
	s_nop 0
	v_lshl_add_u64 v[132:133], v[154:155], 2, s[4:5]
	s_and_saveexec_b64 s[22:23], vcc
	s_cbranch_execz .LBB0_845
	v_lshl_add_u64 v[134:135], s[66:67], 2, v[132:133]
	v_mov_b32_e32 v129, v185
	v_lshl_add_u64 v[134:135], v[134:135], 0, v[128:129]
	global_store_dwordx4 v[134:135], v[108:111], off nt
	global_store_dwordx4 v[134:135], v[104:107], off offset:16 nt
.LBB0_845:
	s_or_b64 exec, exec, s[22:23]
	v_cvt_pk_bf16_f32 v152, v100, v101
	v_cvt_pk_bf16_f32 v153, v102, v103
	v_cvt_pk_bf16_f32 v154, v96, v97
	v_cvt_pk_bf16_f32 v155, v98, v99
	global_store_dwordx4 v[130:131], v[152:155], off offset:256
	s_and_saveexec_b64 s[22:23], vcc
	s_cbranch_execz .LBB0_847
	v_lshl_add_u64 v[130:131], s[66:67], 2, v[132:133]
	v_mov_b32_e32 v129, v185
	v_lshl_add_u64 v[130:131], v[130:131], 0, v[128:129]
	global_store_dwordx4 v[130:131], v[100:103], off offset:512 nt
	global_store_dwordx4 v[130:131], v[96:99], off offset:528 nt
.LBB0_847:
	s_or_b64 exec, exec, s[22:23]
	v_add_u32_e32 v152, s38, v181
	v_ashrrev_i32_e32 v153, 31, v152
	v_lshlrev_b64 v[130:131], 11, v[152:153]
	v_lshl_add_u64 v[130:131], s[12:13], 0, v[130:131]
	v_lshl_add_u64 v[130:131], s[66:67], 1, v[130:131]
	v_lshlrev_b64 v[154:155], 10, v[152:153]
	v_lshl_add_u64 v[130:131], v[130:131], 0, v[184:185]
	v_cvt_pk_bf16_f32 v132, v92, v93
	v_cvt_pk_bf16_f32 v133, v94, v95
	v_cvt_pk_bf16_f32 v134, v88, v89
	v_cvt_pk_bf16_f32 v135, v90, v91
	global_store_dwordx4 v[130:131], v[132:135], off
	v_cmp_gt_i32_e32 vcc, s41, v152
	s_nop 0
	v_lshl_add_u64 v[132:133], v[154:155], 2, s[4:5]
	s_and_saveexec_b64 s[22:23], vcc
	s_cbranch_execz .LBB0_849
	v_lshl_add_u64 v[134:135], s[66:67], 2, v[132:133]
	v_mov_b32_e32 v129, v185
	v_lshl_add_u64 v[134:135], v[134:135], 0, v[128:129]
	global_store_dwordx4 v[134:135], v[92:95], off nt
	global_store_dwordx4 v[134:135], v[88:91], off offset:16 nt
.LBB0_849:
	s_or_b64 exec, exec, s[22:23]
	v_cvt_pk_bf16_f32 v152, v84, v85
	v_cvt_pk_bf16_f32 v153, v86, v87
	v_cvt_pk_bf16_f32 v154, v80, v81
	v_cvt_pk_bf16_f32 v155, v82, v83
	global_store_dwordx4 v[130:131], v[152:155], off offset:256
	s_and_saveexec_b64 s[22:23], vcc
	s_cbranch_execz .LBB0_851
	v_lshl_add_u64 v[130:131], s[66:67], 2, v[132:133]
	v_mov_b32_e32 v129, v185
	v_lshl_add_u64 v[130:131], v[130:131], 0, v[128:129]
	global_store_dwordx4 v[130:131], v[84:87], off offset:512 nt
	global_store_dwordx4 v[130:131], v[80:83], off offset:528 nt
.LBB0_851:
	s_or_b64 exec, exec, s[22:23]
	v_add_u32_e32 v152, s38, v182
	v_ashrrev_i32_e32 v153, 31, v152
	v_lshlrev_b64 v[130:131], 11, v[152:153]
	v_lshl_add_u64 v[130:131], s[12:13], 0, v[130:131]
	v_lshl_add_u64 v[130:131], s[66:67], 1, v[130:131]
	v_lshlrev_b64 v[154:155], 10, v[152:153]
	v_lshl_add_u64 v[130:131], v[130:131], 0, v[184:185]
	v_cvt_pk_bf16_f32 v132, v76, v77
	v_cvt_pk_bf16_f32 v133, v78, v79
	v_cvt_pk_bf16_f32 v134, v72, v73
	v_cvt_pk_bf16_f32 v135, v74, v75
	global_store_dwordx4 v[130:131], v[132:135], off
	v_cmp_gt_i32_e32 vcc, s41, v152
	s_nop 0
	v_lshl_add_u64 v[132:133], v[154:155], 2, s[4:5]
	s_and_saveexec_b64 s[22:23], vcc
	s_cbranch_execz .LBB0_853
	v_lshl_add_u64 v[134:135], s[66:67], 2, v[132:133]
	v_mov_b32_e32 v129, v185
	v_lshl_add_u64 v[134:135], v[134:135], 0, v[128:129]
	global_store_dwordx4 v[134:135], v[76:79], off nt
	global_store_dwordx4 v[134:135], v[72:75], off offset:16 nt
; __device__ __forceinline__ unsigned pk2(float lo, float hi) { f32x2 v = {lo, hi}; bf16x2_hw b = __builtin_convertvector(v, bf16x2_hw); return __builtin_bit_cast(unsigned, b); }
; __device__ __forceinline__ void st_bf8(bf16* p, f32x4 a, f32x4 b) { u32x4 w; w.x = pk2(a[0], a[1]); w.y = pk2(a[2], a[3]); w.z = pk2(b[0], b[1]); w.w = pk2(b[2], b[3]); *(u32x4*)p = w; }
;     __device__ __forceinline__ void operator()(AccRef acc, const pg8::Unit& u, int wr, int wc, int fr, int fq) const {
;     ...
;         else if (t < 8) { const int c0 = (t - 4) * 256; EPI_LOOP_P( st_bf8(KD + rw * 1024 + c0 + cl, v0, v1); if (row < nvalid) { float* o = okd + rw * 1024 + c0 + cl; *(f32x4*)o = v0; *(f32x4*)(o + 4) = v1; } ) }
.LBB0_853:
	s_or_b64 exec, exec, s[22:23]
	v_cvt_pk_bf16_f32 v152, v68, v69
	v_cvt_pk_bf16_f32 v153, v70, v71
	v_cvt_pk_bf16_f32 v154, v64, v65
	v_cvt_pk_bf16_f32 v155, v66, v67
	global_store_dwordx4 v[130:131], v[152:155], off offset:256
	s_and_saveexec_b64 s[22:23], vcc
	s_cbranch_execz .LBB0_855
	v_lshl_add_u64 v[130:131], s[66:67], 2, v[132:133]
	v_mov_b32_e32 v129, v185
	v_lshl_add_u64 v[130:131], v[130:131], 0, v[128:129]
	global_store_dwordx4 v[130:131], v[68:71], off offset:512 nt
	global_store_dwordx4 v[130:131], v[64:67], off offset:528 nt
.LBB0_855:
	s_or_b64 exec, exec, s[22:23]
	v_add_u32_e32 v152, s38, v183
	v_ashrrev_i32_e32 v153, 31, v152
	v_lshlrev_b64 v[130:131], 11, v[152:153]
	v_lshl_add_u64 v[130:131], s[12:13], 0, v[130:131]
	v_lshl_add_u64 v[130:131], s[66:67], 1, v[130:131]
	v_lshlrev_b64 v[154:155], 10, v[152:153]
	v_lshl_add_u64 v[130:131], v[130:131], 0, v[184:185]
	v_cvt_pk_bf16_f32 v132, v60, v61
	v_cvt_pk_bf16_f32 v133, v62, v63
	v_cvt_pk_bf16_f32 v134, v56, v57
	v_cvt_pk_bf16_f32 v135, v58, v59
	global_store_dwordx4 v[130:131], v[132:135], off
	v_cmp_gt_i32_e32 vcc, s41, v152
	s_nop 0
	v_lshl_add_u64 v[132:133], v[154:155], 2, s[4:5]
	s_and_saveexec_b64 s[22:23], vcc
	s_cbranch_execz .LBB0_857
	v_lshl_add_u64 v[134:135], s[66:67], 2, v[132:133]
	v_mov_b32_e32 v129, v185
	v_lshl_add_u64 v[134:135], v[134:135], 0, v[128:129]
	global_store_dwordx4 v[134:135], v[60:63], off nt
	global_store_dwordx4 v[134:135], v[56:59], off offset:16 nt
.LBB0_857:
	s_or_b64 exec, exec, s[22:23]
	v_cvt_pk_bf16_f32 v152, v52, v53
	v_cvt_pk_bf16_f32 v153, v54, v55
	v_cvt_pk_bf16_f32 v154, v48, v49
	v_cvt_pk_bf16_f32 v155, v50, v51
	global_store_dwordx4 v[130:131], v[152:155], off offset:256
	s_and_saveexec_b64 s[22:23], vcc
	s_cbranch_execz .LBB0_859
	v_lshl_add_u64 v[130:131], s[66:67], 2, v[132:133]
	v_mov_b32_e32 v129, v185
	v_lshl_add_u64 v[130:131], v[130:131], 0, v[128:129]
	global_store_dwordx4 v[130:131], v[52:55], off offset:512 nt
	global_store_dwordx4 v[130:131], v[48:51], off offset:528 nt
.LBB0_859:
	s_or_b64 exec, exec, s[22:23]
	v_add_u32_e32 v152, s38, v190
	v_ashrrev_i32_e32 v153, 31, v152
	v_lshlrev_b64 v[130:131], 11, v[152:153]
	v_lshl_add_u64 v[130:131], s[12:13], 0, v[130:131]
	v_lshl_add_u64 v[130:131], s[66:67], 1, v[130:131]
	v_lshlrev_b64 v[154:155], 10, v[152:153]
	v_lshl_add_u64 v[130:131], v[130:131], 0, v[184:185]
	v_cvt_pk_bf16_f32 v132, v44, v45
	v_cvt_pk_bf16_f32 v133, v46, v47
	v_cvt_pk_bf16_f32 v134, v40, v41
	v_cvt_pk_bf16_f32 v135, v42, v43
	global_store_dwordx4 v[130:131], v[132:135], off
	v_cmp_gt_i32_e32 vcc, s41, v152
	s_nop 0
	v_lshl_add_u64 v[132:133], v[154:155], 2, s[4:5]
	s_and_saveexec_b64 s[22:23], vcc
	s_cbranch_execz .LBB0_861
	v_lshl_add_u64 v[134:135], s[66:67], 2, v[132:133]
	v_mov_b32_e32 v129, v185
	v_lshl_add_u64 v[134:135], v[134:135], 0, v[128:129]
	global_store_dwordx4 v[134:135], v[44:47], off nt
	global_store_dwordx4 v[134:135], v[40:43], off offset:16 nt
.LBB0_861:
	s_or_b64 exec, exec, s[22:23]
	v_cvt_pk_bf16_f32 v152, v36, v37
	v_cvt_pk_bf16_f32 v153, v38, v39
	v_cvt_pk_bf16_f32 v154, v32, v33
	v_cvt_pk_bf16_f32 v155, v34, v35
	global_store_dwordx4 v[130:131], v[152:155], off offset:256
	s_and_saveexec_b64 s[22:23], vcc
	s_cbranch_execz .LBB0_863
	v_lshl_add_u64 v[130:131], s[66:67], 2, v[132:133]
	v_mov_b32_e32 v129, v185
	v_lshl_add_u64 v[130:131], v[130:131], 0, v[128:129]
	global_store_dwordx4 v[130:131], v[36:39], off offset:512 nt
	global_store_dwordx4 v[130:131], v[32:35], off offset:528 nt
.LBB0_863:
	s_or_b64 exec, exec, s[22:23]
	v_add_u32_e32 v152, s38, v191
	v_ashrrev_i32_e32 v153, 31, v152
	v_lshlrev_b64 v[130:131], 11, v[152:153]
	v_lshl_add_u64 v[130:131], s[12:13], 0, v[130:131]
	v_lshl_add_u64 v[130:131], s[66:67], 1, v[130:131]
	v_lshlrev_b64 v[154:155], 10, v[152:153]
	v_lshl_add_u64 v[130:131], v[130:131], 0, v[184:185]
	v_cvt_pk_bf16_f32 v132, v28, v29
	v_cvt_pk_bf16_f32 v133, v30, v31
	v_cvt_pk_bf16_f32 v134, v24, v25
	v_cvt_pk_bf16_f32 v135, v26, v27
	global_store_dwordx4 v[130:131], v[132:135], off
	v_cmp_gt_i32_e32 vcc, s41, v152
	s_nop 0
	v_lshl_add_u64 v[132:133], v[154:155], 2, s[4:5]
	s_and_saveexec_b64 s[22:23], vcc
	s_cbranch_execz .LBB0_865
	v_lshl_add_u64 v[134:135], s[66:67], 2, v[132:133]
	v_mov_b32_e32 v129, v185
	v_lshl_add_u64 v[134:135], v[134:135], 0, v[128:129]
	global_store_dwordx4 v[134:135], v[28:31], off nt
	global_store_dwordx4 v[134:135], v[24:27], off offset:16 nt
.LBB0_865:
	s_or_b64 exec, exec, s[22:23]
	v_cvt_pk_bf16_f32 v152, v20, v21
	v_cvt_pk_bf16_f32 v153, v22, v23
	v_cvt_pk_bf16_f32 v154, v16, v17
	v_cvt_pk_bf16_f32 v155, v18, v19
	global_store_dwordx4 v[130:131], v[152:155], off offset:256
	s_and_saveexec_b64 s[22:23], vcc
	s_cbranch_execz .LBB0_867
	v_lshl_add_u64 v[130:131], s[66:67], 2, v[132:133]
	v_mov_b32_e32 v129, v185
	v_lshl_add_u64 v[130:131], v[130:131], 0, v[128:129]
	global_store_dwordx4 v[130:131], v[20:23], off offset:512 nt
	global_store_dwordx4 v[130:131], v[16:19], off offset:528 nt
.LBB0_867:
	s_or_b64 exec, exec, s[22:23]
	v_add_u32_e32 v152, s38, v192
	v_ashrrev_i32_e32 v153, 31, v152
	v_lshlrev_b64 v[130:131], 11, v[152:153]
	v_lshl_add_u64 v[130:131], s[12:13], 0, v[130:131]
	v_lshl_add_u64 v[130:131], s[66:67], 1, v[130:131]
	v_lshlrev_b64 v[154:155], 10, v[152:153]
	v_lshl_add_u64 v[130:131], v[130:131], 0, v[184:185]
	v_cvt_pk_bf16_f32 v132, v12, v13
	v_cvt_pk_bf16_f32 v133, v14, v15
	v_cvt_pk_bf16_f32 v134, v8, v9
	v_cvt_pk_bf16_f32 v135, v10, v11
	global_store_dwordx4 v[130:131], v[132:135], off
	v_cmp_gt_i32_e32 vcc, s41, v152
	s_nop 0
	v_lshl_add_u64 v[132:133], v[154:155], 2, s[4:5]
	s_and_saveexec_b64 s[22:23], vcc
	s_cbranch_execz .LBB0_869
	v_lshl_add_u64 v[134:135], s[66:67], 2, v[132:133]
	v_mov_b32_e32 v129, v185
	v_lshl_add_u64 v[134:135], v[134:135], 0, v[128:129]
	global_store_dwordx4 v[134:135], v[12:15], off nt
	global_store_dwordx4 v[134:135], v[8:11], off offset:16 nt
.LBB0_869:
	s_or_b64 exec, exec, s[22:23]
	v_cvt_pk_bf16_f32 v152, v4, v5
	v_cvt_pk_bf16_f32 v153, v6, v7
	v_cvt_pk_bf16_f32 v154, v0, v1
	v_cvt_pk_bf16_f32 v155, v2, v3
	global_store_dwordx4 v[130:131], v[152:155], off offset:256
	s_and_saveexec_b64 s[22:23], vcc
	s_cbranch_execz .LBB0_871
	v_lshl_add_u64 v[130:131], s[66:67], 2, v[132:133]
	v_mov_b32_e32 v129, v185
	v_lshl_add_u64 v[128:129], v[130:131], 0, v[128:129]
	global_store_dwordx4 v[128:129], v[4:7], off offset:512 nt
	global_store_dwordx4 v[128:129], v[0:3], off offset:528 nt
